# grid barrier: two polls of the arrival counter kept in flight
# baseline (speedup 1.0000x reference)
.Lbar_wait:
	s_mov_b32 s24, 0
	global_load_dword v4, v26, s[8:9] sc1
.Lbar_spin:
	global_load_dword v6, v26, s[8:9] sc1
	s_add_i32 s24, s24, 1
	s_waitcnt vmcnt(1)
	v_cmp_ge_u32_e32 vcc, v4, v5
	s_cbranch_vccnz .Lbar_done
	global_load_dword v4, v26, s[8:9] sc1
	s_waitcnt vmcnt(1)
	v_cmp_ge_u32_e32 vcc, v6, v5
	s_cbranch_vccnz .Lbar_done
	s_and_b32 s10, s24, 0xff
	s_cmp_lg_u32 s10, 0
	s_cbranch_scc1 .Lbar_spin
	global_load_dword v6, v26, s[60:61] sc1
	s_waitcnt vmcnt(0)
	v_cmp_ne_u32_e32 vcc, 0, v6
	s_cbranch_vccnz .Lbar_done
	s_cmp_lt_u32 s24, 0x80001
	s_cbranch_scc1 .Lbar_spin
	global_atomic_add v26, v228, s[60:61]
